# prep ring depth 2; exact vmcnt(8) at attention loop bottom; mem-attention gate loads hoisted
# baseline (speedup 1.0000x reference)
.Lprep_ld_rows:
	s_lshl_b32 s36, s33, 12
	s_add_u32 s36, s4, s36
	s_addc_u32 s37, s5, 0
	global_load_dwordx4 v[96:99], v6, s[36:37] nt
	global_load_dwordx4 v[100:103], v6, s[36:37] offset:1024 nt
	global_load_dwordx4 v[104:107], v6, s[36:37] offset:2048 nt
	global_load_dwordx4 v[108:111], v6, s[36:37] offset:3072 nt
	s_add_u32 s36, s36, 0x800000
	s_addc_u32 s37, s37, 0
	global_load_dwordx4 v[112:115], v6, s[36:37] nt
	global_load_dwordx4 v[116:119], v6, s[36:37] offset:1024 nt
	global_load_dwordx4 v[120:123], v6, s[36:37] offset:2048 nt
	global_load_dwordx4 v[124:127], v6, s[36:37] offset:3072 nt
	s_add_u32 s36, s36, 0x800000
	s_addc_u32 s37, s37, 0
	s_waitcnt vmcnt(8)

.Lprep_rows:
	v_mov_b32_e32 v17, 0x358637bd
	s_lshl_b32 s56, s33, 11
	s_add_u32 s56, s28, s56
	s_addc_u32 s57, s29, 0
	s_cmpk_lt_u32 s2, 0x80
	s_cbranch_scc0 .Lprep_rows8
	s_waitcnt vmcnt(12)
	v_pk_mul_f32 v[240:241], v[96:97], v[96:97]
	v_pk_mul_f32 v[242:243], v[104:105], v[104:105]
	v_pk_fma_f32 v[240:241], v[98:99], v[98:99], v[240:241]
	v_pk_fma_f32 v[242:243], v[106:107], v[106:107], v[242:243]
	v_pk_fma_f32 v[240:241], v[100:101], v[100:101], v[240:241]
	v_pk_fma_f32 v[242:243], v[108:109], v[108:109], v[242:243]
	v_pk_fma_f32 v[240:241], v[102:103], v[102:103], v[240:241]
	v_pk_fma_f32 v[242:243], v[110:111], v[110:111], v[242:243]
	v_pk_add_f32 v[240:241], v[240:241], v[242:243]
	s_nop 0
	v_add_f32_e32 v244, v240, v241
	s_nop 1
	v_add_f32_dpp v244, v244, v244 quad_perm:[1,0,3,2] row_mask:0xf bank_mask:0xf
	s_nop 1
	v_add_f32_dpp v244, v244, v244 quad_perm:[2,3,0,1] row_mask:0xf bank_mask:0xf
	s_nop 1
	v_add_f32_dpp v244, v244, v244 row_half_mirror row_mask:0xf bank_mask:0xf
	s_nop 1
	v_add_f32_dpp v244, v244, v244 row_mirror row_mask:0xf bank_mask:0xf
	s_nop 1
	v_readlane_b32 s38, v244, 0
	v_readlane_b32 s39, v244, 16
	v_readlane_b32 s40, v244, 32
	v_readlane_b32 s41, v244, 48
	s_nop 1
	v_mov_b32_e32 v246, s38
	v_add_f32_e32 v246, s39, v246
	v_add_f32_e32 v246, s40, v246
	v_add_f32_e32 v246, s41, v246
	v_fmamk_f32 v246, v246, 0x3a800000, v17
	v_rsq_f32_e32 v246, v246
	s_nop 0
	v_pk_mul_f32 v[96:97], v[96:97], v[246:247] op_sel_hi:[1,0]
	v_pk_mul_f32 v[98:99], v[98:99], v[246:247] op_sel_hi:[1,0]
	v_pk_mul_f32 v[100:101], v[100:101], v[246:247] op_sel_hi:[1,0]
	v_pk_mul_f32 v[102:103], v[102:103], v[246:247] op_sel_hi:[1,0]
	v_pk_mul_f32 v[104:105], v[104:105], v[246:247] op_sel_hi:[1,0]
	v_pk_mul_f32 v[106:107], v[106:107], v[246:247] op_sel_hi:[1,0]
	v_pk_mul_f32 v[108:109], v[108:109], v[246:247] op_sel_hi:[1,0]
	v_pk_mul_f32 v[110:111], v[110:111], v[246:247] op_sel_hi:[1,0]
	v_cvt_pk_bf16_f32 v96, v96, v97
	v_cvt_pk_bf16_f32 v97, v98, v99
	v_cvt_pk_bf16_f32 v98, v100, v101
	v_cvt_pk_bf16_f32 v99, v102, v103
	v_cvt_pk_bf16_f32 v100, v104, v105
	v_cvt_pk_bf16_f32 v101, v106, v107
	v_cvt_pk_bf16_f32 v102, v108, v109
	v_cvt_pk_bf16_f32 v103, v110, v111
	global_store_dwordx2 v11, v[96:97], s[56:57]
	global_store_dwordx2 v11, v[98:99], s[56:57] offset:512
	global_store_dwordx2 v11, v[100:101], s[56:57] offset:1024
	global_store_dwordx2 v11, v[102:103], s[56:57] offset:1536
	s_add_u32 s56, s56, 0x400000
	s_addc_u32 s57, s57, 0
	global_load_dwordx4 v[96:99], v6, s[36:37] nt
	global_load_dwordx4 v[100:103], v6, s[36:37] offset:1024 nt
	global_load_dwordx4 v[104:107], v6, s[36:37] offset:2048 nt
	global_load_dwordx4 v[108:111], v6, s[36:37] offset:3072 nt
	s_add_u32 s36, s36, 0x800000
	s_addc_u32 s37, s37, 0
	s_waitcnt vmcnt(16)
	v_pk_mul_f32 v[240:241], v[112:113], v[112:113]
	v_pk_mul_f32 v[242:243], v[120:121], v[120:121]
	v_pk_fma_f32 v[240:241], v[114:115], v[114:115], v[240:241]
	v_pk_fma_f32 v[242:243], v[122:123], v[122:123], v[242:243]
	v_pk_fma_f32 v[240:241], v[116:117], v[116:117], v[240:241]
	v_pk_fma_f32 v[242:243], v[124:125], v[124:125], v[242:243]
	v_pk_fma_f32 v[240:241], v[118:119], v[118:119], v[240:241]
	v_pk_fma_f32 v[242:243], v[126:127], v[126:127], v[242:243]
	v_pk_add_f32 v[240:241], v[240:241], v[242:243]
	s_nop 0
	v_add_f32_e32 v244, v240, v241
	s_nop 1
	v_add_f32_dpp v244, v244, v244 quad_perm:[1,0,3,2] row_mask:0xf bank_mask:0xf
	s_nop 1
	v_add_f32_dpp v244, v244, v244 quad_perm:[2,3,0,1] row_mask:0xf bank_mask:0xf
	s_nop 1
	v_add_f32_dpp v244, v244, v244 row_half_mirror row_mask:0xf bank_mask:0xf
	s_nop 1
	v_add_f32_dpp v244, v244, v244 row_mirror row_mask:0xf bank_mask:0xf
	s_nop 1
	v_readlane_b32 s38, v244, 0
	v_readlane_b32 s39, v244, 16
	v_readlane_b32 s40, v244, 32
	v_readlane_b32 s41, v244, 48
	s_nop 1
	v_mov_b32_e32 v246, s38
	v_add_f32_e32 v246, s39, v246
	v_add_f32_e32 v246, s40, v246
	v_add_f32_e32 v246, s41, v246
	v_fmamk_f32 v246, v246, 0x3a800000, v17
	v_rsq_f32_e32 v246, v246
	s_nop 0
	v_pk_mul_f32 v[112:113], v[112:113], v[246:247] op_sel_hi:[1,0]
	v_pk_mul_f32 v[114:115], v[114:115], v[246:247] op_sel_hi:[1,0]
	v_pk_mul_f32 v[116:117], v[116:117], v[246:247] op_sel_hi:[1,0]
	v_pk_mul_f32 v[118:119], v[118:119], v[246:247] op_sel_hi:[1,0]
	v_pk_mul_f32 v[120:121], v[120:121], v[246:247] op_sel_hi:[1,0]
	v_pk_mul_f32 v[122:123], v[122:123], v[246:247] op_sel_hi:[1,0]
	v_pk_mul_f32 v[124:125], v[124:125], v[246:247] op_sel_hi:[1,0]
	v_pk_mul_f32 v[126:127], v[126:127], v[246:247] op_sel_hi:[1,0]
	v_cvt_pk_bf16_f32 v112, v112, v113
	v_cvt_pk_bf16_f32 v113, v114, v115
	v_cvt_pk_bf16_f32 v114, v116, v117
	v_cvt_pk_bf16_f32 v115, v118, v119
	v_cvt_pk_bf16_f32 v116, v120, v121
	v_cvt_pk_bf16_f32 v117, v122, v123
	v_cvt_pk_bf16_f32 v118, v124, v125
	v_cvt_pk_bf16_f32 v119, v126, v127
	global_store_dwordx2 v11, v[112:113], s[56:57]
	global_store_dwordx2 v11, v[114:115], s[56:57] offset:512
	global_store_dwordx2 v11, v[116:117], s[56:57] offset:1024
	global_store_dwordx2 v11, v[118:119], s[56:57] offset:1536
	s_add_u32 s56, s56, 0x400000
	s_addc_u32 s57, s57, 0
	global_load_dwordx4 v[112:115], v6, s[36:37] nt
	global_load_dwordx4 v[116:119], v6, s[36:37] offset:1024 nt
	global_load_dwordx4 v[120:123], v6, s[36:37] offset:2048 nt
	global_load_dwordx4 v[124:127], v6, s[36:37] offset:3072 nt
	s_add_u32 s36, s36, 0x800000
	s_addc_u32 s37, s37, 0
	s_waitcnt vmcnt(8)
	v_pk_mul_f32 v[240:241], v[96:97], v[96:97]
	v_pk_mul_f32 v[242:243], v[104:105], v[104:105]
	v_pk_fma_f32 v[240:241], v[98:99], v[98:99], v[240:241]
	v_pk_fma_f32 v[242:243], v[106:107], v[106:107], v[242:243]
	v_pk_fma_f32 v[240:241], v[100:101], v[100:101], v[240:241]
	v_pk_fma_f32 v[242:243], v[108:109], v[108:109], v[242:243]
	v_pk_fma_f32 v[240:241], v[102:103], v[102:103], v[240:241]
	v_pk_fma_f32 v[242:243], v[110:111], v[110:111], v[242:243]
	v_pk_add_f32 v[240:241], v[240:241], v[242:243]
	s_nop 0
	v_add_f32_e32 v244, v240, v241
	s_nop 1
	v_add_f32_dpp v244, v244, v244 quad_perm:[1,0,3,2] row_mask:0xf bank_mask:0xf
	s_nop 1
	v_add_f32_dpp v244, v244, v244 quad_perm:[2,3,0,1] row_mask:0xf bank_mask:0xf
	s_nop 1
	v_add_f32_dpp v244, v244, v244 row_half_mirror row_mask:0xf bank_mask:0xf
	s_nop 1
	v_add_f32_dpp v244, v244, v244 row_mirror row_mask:0xf bank_mask:0xf
	s_nop 1
	v_readlane_b32 s38, v244, 0
	v_readlane_b32 s39, v244, 16
	v_readlane_b32 s40, v244, 32
	v_readlane_b32 s41, v244, 48
	s_nop 1
	v_mov_b32_e32 v246, s38
	v_add_f32_e32 v246, s39, v246
	v_add_f32_e32 v246, s40, v246
	v_add_f32_e32 v246, s41, v246
	v_fmamk_f32 v246, v246, 0x3a800000, v17
	v_rsq_f32_e32 v246, v246
	s_nop 0
	v_pk_mul_f32 v[96:97], v[96:97], v[246:247] op_sel_hi:[1,0]
	v_pk_mul_f32 v[98:99], v[98:99], v[246:247] op_sel_hi:[1,0]
	v_pk_mul_f32 v[100:101], v[100:101], v[246:247] op_sel_hi:[1,0]
	v_pk_mul_f32 v[102:103], v[102:103], v[246:247] op_sel_hi:[1,0]
	v_pk_mul_f32 v[104:105], v[104:105], v[246:247] op_sel_hi:[1,0]
	v_pk_mul_f32 v[106:107], v[106:107], v[246:247] op_sel_hi:[1,0]
	v_pk_mul_f32 v[108:109], v[108:109], v[246:247] op_sel_hi:[1,0]
	v_pk_mul_f32 v[110:111], v[110:111], v[246:247] op_sel_hi:[1,0]
	v_cvt_pk_bf16_f32 v96, v96, v97
	v_cvt_pk_bf16_f32 v97, v98, v99
	v_cvt_pk_bf16_f32 v98, v100, v101
	v_cvt_pk_bf16_f32 v99, v102, v103
	v_cvt_pk_bf16_f32 v100, v104, v105
	v_cvt_pk_bf16_f32 v101, v106, v107
	v_cvt_pk_bf16_f32 v102, v108, v109
	v_cvt_pk_bf16_f32 v103, v110, v111
	global_store_dwordx2 v11, v[96:97], s[56:57]
	global_store_dwordx2 v11, v[98:99], s[56:57] offset:512
	global_store_dwordx2 v11, v[100:101], s[56:57] offset:1024
	global_store_dwordx2 v11, v[102:103], s[56:57] offset:1536
	s_add_u32 s56, s56, 0x400000
	s_addc_u32 s57, s57, 0
	global_load_dwordx4 v[96:99], v6, s[36:37] nt
	global_load_dwordx4 v[100:103], v6, s[36:37] offset:1024 nt
	global_load_dwordx4 v[104:107], v6, s[36:37] offset:2048 nt
	global_load_dwordx4 v[108:111], v6, s[36:37] offset:3072 nt
	s_add_u32 s36, s36, 0x800000
	s_addc_u32 s37, s37, 0
	s_waitcnt vmcnt(8)
	v_pk_mul_f32 v[240:241], v[112:113], v[112:113]
	v_pk_mul_f32 v[242:243], v[120:121], v[120:121]
	v_pk_fma_f32 v[240:241], v[114:115], v[114:115], v[240:241]
	v_pk_fma_f32 v[242:243], v[122:123], v[122:123], v[242:243]
	v_pk_fma_f32 v[240:241], v[116:117], v[116:117], v[240:241]
	v_pk_fma_f32 v[242:243], v[124:125], v[124:125], v[242:243]
	v_pk_fma_f32 v[240:241], v[118:119], v[118:119], v[240:241]
	v_pk_fma_f32 v[242:243], v[126:127], v[126:127], v[242:243]
	v_pk_add_f32 v[240:241], v[240:241], v[242:243]
	s_nop 0
	v_add_f32_e32 v244, v240, v241
	s_nop 1
	v_add_f32_dpp v244, v244, v244 quad_perm:[1,0,3,2] row_mask:0xf bank_mask:0xf
	s_nop 1
	v_add_f32_dpp v244, v244, v244 quad_perm:[2,3,0,1] row_mask:0xf bank_mask:0xf
	s_nop 1
	v_add_f32_dpp v244, v244, v244 row_half_mirror row_mask:0xf bank_mask:0xf
	s_nop 1
	v_add_f32_dpp v244, v244, v244 row_mirror row_mask:0xf bank_mask:0xf
	s_nop 1
	v_readlane_b32 s38, v244, 0
	v_readlane_b32 s39, v244, 16
	v_readlane_b32 s40, v244, 32
	v_readlane_b32 s41, v244, 48
	s_nop 1
	v_mov_b32_e32 v246, s38
	v_add_f32_e32 v246, s39, v246
	v_add_f32_e32 v246, s40, v246
	v_add_f32_e32 v246, s41, v246
	v_fmamk_f32 v246, v246, 0x3a800000, v17
	v_rsq_f32_e32 v246, v246
	s_nop 0
	v_pk_mul_f32 v[112:113], v[112:113], v[246:247] op_sel_hi:[1,0]
	v_pk_mul_f32 v[114:115], v[114:115], v[246:247] op_sel_hi:[1,0]
	v_pk_mul_f32 v[116:117], v[116:117], v[246:247] op_sel_hi:[1,0]
	v_pk_mul_f32 v[118:119], v[118:119], v[246:247] op_sel_hi:[1,0]
	v_pk_mul_f32 v[120:121], v[120:121], v[246:247] op_sel_hi:[1,0]
	v_pk_mul_f32 v[122:123], v[122:123], v[246:247] op_sel_hi:[1,0]
	v_pk_mul_f32 v[124:125], v[124:125], v[246:247] op_sel_hi:[1,0]
	v_pk_mul_f32 v[126:127], v[126:127], v[246:247] op_sel_hi:[1,0]
	v_cvt_pk_bf16_f32 v112, v112, v113
	v_cvt_pk_bf16_f32 v113, v114, v115
	v_cvt_pk_bf16_f32 v114, v116, v117
	v_cvt_pk_bf16_f32 v115, v118, v119
	v_cvt_pk_bf16_f32 v116, v120, v121
	v_cvt_pk_bf16_f32 v117, v122, v123
	v_cvt_pk_bf16_f32 v118, v124, v125
	v_cvt_pk_bf16_f32 v119, v126, v127
	global_store_dwordx2 v11, v[112:113], s[56:57]
	global_store_dwordx2 v11, v[114:115], s[56:57] offset:512
	global_store_dwordx2 v11, v[116:117], s[56:57] offset:1024
	global_store_dwordx2 v11, v[118:119], s[56:57] offset:1536
	s_add_u32 s56, s56, 0x400000
	s_addc_u32 s57, s57, 0
	global_load_dwordx4 v[112:115], v6, s[36:37] nt
	global_load_dwordx4 v[116:119], v6, s[36:37] offset:1024 nt
	global_load_dwordx4 v[120:123], v6, s[36:37] offset:2048 nt
	global_load_dwordx4 v[124:127], v6, s[36:37] offset:3072 nt
	s_add_u32 s36, s36, 0x800000
	s_addc_u32 s37, s37, 0
	s_waitcnt vmcnt(8)
	v_pk_mul_f32 v[240:241], v[96:97], v[96:97]
	v_pk_mul_f32 v[242:243], v[104:105], v[104:105]
	v_pk_fma_f32 v[240:241], v[98:99], v[98:99], v[240:241]
	v_pk_fma_f32 v[242:243], v[106:107], v[106:107], v[242:243]
	v_pk_fma_f32 v[240:241], v[100:101], v[100:101], v[240:241]
	v_pk_fma_f32 v[242:243], v[108:109], v[108:109], v[242:243]
	v_pk_fma_f32 v[240:241], v[102:103], v[102:103], v[240:241]
	v_pk_fma_f32 v[242:243], v[110:111], v[110:111], v[242:243]
	v_pk_add_f32 v[240:241], v[240:241], v[242:243]
	s_nop 0
	v_add_f32_e32 v244, v240, v241
	s_nop 1
	v_add_f32_dpp v244, v244, v244 quad_perm:[1,0,3,2] row_mask:0xf bank_mask:0xf
	s_nop 1
	v_add_f32_dpp v244, v244, v244 quad_perm:[2,3,0,1] row_mask:0xf bank_mask:0xf
	s_nop 1
	v_add_f32_dpp v244, v244, v244 row_half_mirror row_mask:0xf bank_mask:0xf
	s_nop 1
	v_add_f32_dpp v244, v244, v244 row_mirror row_mask:0xf bank_mask:0xf
	s_nop 1
	v_readlane_b32 s38, v244, 0
	v_readlane_b32 s39, v244, 16
	v_readlane_b32 s40, v244, 32
	v_readlane_b32 s41, v244, 48
	s_nop 1
	v_mov_b32_e32 v246, s38
	v_add_f32_e32 v246, s39, v246
	v_add_f32_e32 v246, s40, v246
	v_add_f32_e32 v246, s41, v246
	v_fmamk_f32 v246, v246, 0x3a800000, v17
	v_rsq_f32_e32 v246, v246
	s_nop 0
	v_pk_mul_f32 v[96:97], v[96:97], v[246:247] op_sel_hi:[1,0]
	v_pk_mul_f32 v[98:99], v[98:99], v[246:247] op_sel_hi:[1,0]
	v_pk_mul_f32 v[100:101], v[100:101], v[246:247] op_sel_hi:[1,0]
	v_pk_mul_f32 v[102:103], v[102:103], v[246:247] op_sel_hi:[1,0]
	v_pk_mul_f32 v[104:105], v[104:105], v[246:247] op_sel_hi:[1,0]
	v_pk_mul_f32 v[106:107], v[106:107], v[246:247] op_sel_hi:[1,0]
	v_pk_mul_f32 v[108:109], v[108:109], v[246:247] op_sel_hi:[1,0]
	v_pk_mul_f32 v[110:111], v[110:111], v[246:247] op_sel_hi:[1,0]
	v_cvt_pk_bf16_f32 v96, v96, v97
	v_cvt_pk_bf16_f32 v97, v98, v99
	v_cvt_pk_bf16_f32 v98, v100, v101
	v_cvt_pk_bf16_f32 v99, v102, v103
	v_cvt_pk_bf16_f32 v100, v104, v105
	v_cvt_pk_bf16_f32 v101, v106, v107
	v_cvt_pk_bf16_f32 v102, v108, v109
	v_cvt_pk_bf16_f32 v103, v110, v111
	global_store_dwordx2 v11, v[96:97], s[56:57]
	global_store_dwordx2 v11, v[98:99], s[56:57] offset:512
	global_store_dwordx2 v11, v[100:101], s[56:57] offset:1024
	global_store_dwordx2 v11, v[102:103], s[56:57] offset:1536
	s_add_u32 s56, s56, 0x400000
	s_addc_u32 s57, s57, 0
	global_load_dwordx4 v[96:99], v6, s[36:37] nt
	global_load_dwordx4 v[100:103], v6, s[36:37] offset:1024 nt
	global_load_dwordx4 v[104:107], v6, s[36:37] offset:2048 nt
	global_load_dwordx4 v[108:111], v6, s[36:37] offset:3072 nt
	s_add_u32 s36, s36, 0x800000
	s_addc_u32 s37, s37, 0
	s_waitcnt vmcnt(8)
	v_pk_mul_f32 v[240:241], v[112:113], v[112:113]
	v_pk_mul_f32 v[242:243], v[120:121], v[120:121]
	v_pk_fma_f32 v[240:241], v[114:115], v[114:115], v[240:241]
	v_pk_fma_f32 v[242:243], v[122:123], v[122:123], v[242:243]
	v_pk_fma_f32 v[240:241], v[116:117], v[116:117], v[240:241]
	v_pk_fma_f32 v[242:243], v[124:125], v[124:125], v[242:243]
	v_pk_fma_f32 v[240:241], v[118:119], v[118:119], v[240:241]
	v_pk_fma_f32 v[242:243], v[126:127], v[126:127], v[242:243]
	v_pk_add_f32 v[240:241], v[240:241], v[242:243]
	s_nop 0
	v_add_f32_e32 v244, v240, v241
	s_nop 1
	v_add_f32_dpp v244, v244, v244 quad_perm:[1,0,3,2] row_mask:0xf bank_mask:0xf
	s_nop 1
	v_add_f32_dpp v244, v244, v244 quad_perm:[2,3,0,1] row_mask:0xf bank_mask:0xf
	s_nop 1
	v_add_f32_dpp v244, v244, v244 row_half_mirror row_mask:0xf bank_mask:0xf
	s_nop 1
	v_add_f32_dpp v244, v244, v244 row_mirror row_mask:0xf bank_mask:0xf
	s_nop 1
	v_readlane_b32 s38, v244, 0
	v_readlane_b32 s39, v244, 16
	v_readlane_b32 s40, v244, 32
	v_readlane_b32 s41, v244, 48
	s_nop 1
	v_mov_b32_e32 v246, s38
	v_add_f32_e32 v246, s39, v246
	v_add_f32_e32 v246, s40, v246
	v_add_f32_e32 v246, s41, v246
	v_fmamk_f32 v246, v246, 0x3a800000, v17
	v_rsq_f32_e32 v246, v246
	s_nop 0
	v_pk_mul_f32 v[112:113], v[112:113], v[246:247] op_sel_hi:[1,0]
	v_pk_mul_f32 v[114:115], v[114:115], v[246:247] op_sel_hi:[1,0]
	v_pk_mul_f32 v[116:117], v[116:117], v[246:247] op_sel_hi:[1,0]
	v_pk_mul_f32 v[118:119], v[118:119], v[246:247] op_sel_hi:[1,0]
	v_pk_mul_f32 v[120:121], v[120:121], v[246:247] op_sel_hi:[1,0]
	v_pk_mul_f32 v[122:123], v[122:123], v[246:247] op_sel_hi:[1,0]
	v_pk_mul_f32 v[124:125], v[124:125], v[246:247] op_sel_hi:[1,0]
	v_pk_mul_f32 v[126:127], v[126:127], v[246:247] op_sel_hi:[1,0]
	v_cvt_pk_bf16_f32 v112, v112, v113
	v_cvt_pk_bf16_f32 v113, v114, v115
	v_cvt_pk_bf16_f32 v114, v116, v117
	v_cvt_pk_bf16_f32 v115, v118, v119
	v_cvt_pk_bf16_f32 v116, v120, v121
	v_cvt_pk_bf16_f32 v117, v122, v123
	v_cvt_pk_bf16_f32 v118, v124, v125
	v_cvt_pk_bf16_f32 v119, v126, v127
	global_store_dwordx2 v11, v[112:113], s[56:57]
	global_store_dwordx2 v11, v[114:115], s[56:57] offset:512
	global_store_dwordx2 v11, v[116:117], s[56:57] offset:1024
	global_store_dwordx2 v11, v[118:119], s[56:57] offset:1536
	s_add_u32 s56, s56, 0x400000
	s_addc_u32 s57, s57, 0
	global_load_dwordx4 v[112:115], v6, s[36:37] nt
	global_load_dwordx4 v[116:119], v6, s[36:37] offset:1024 nt
	global_load_dwordx4 v[120:123], v6, s[36:37] offset:2048 nt
	global_load_dwordx4 v[124:127], v6, s[36:37] offset:3072 nt
	s_waitcnt vmcnt(8)
	v_pk_mul_f32 v[240:241], v[96:97], v[96:97]
	v_pk_mul_f32 v[242:243], v[104:105], v[104:105]
	v_pk_fma_f32 v[240:241], v[98:99], v[98:99], v[240:241]
	v_pk_fma_f32 v[242:243], v[106:107], v[106:107], v[242:243]
	v_pk_fma_f32 v[240:241], v[100:101], v[100:101], v[240:241]
	v_pk_fma_f32 v[242:243], v[108:109], v[108:109], v[242:243]
	v_pk_fma_f32 v[240:241], v[102:103], v[102:103], v[240:241]
	v_pk_fma_f32 v[242:243], v[110:111], v[110:111], v[242:243]
	v_pk_add_f32 v[240:241], v[240:241], v[242:243]
	s_nop 0
	v_add_f32_e32 v244, v240, v241
	s_nop 1
	v_add_f32_dpp v244, v244, v244 quad_perm:[1,0,3,2] row_mask:0xf bank_mask:0xf
	s_nop 1
	v_add_f32_dpp v244, v244, v244 quad_perm:[2,3,0,1] row_mask:0xf bank_mask:0xf
	s_nop 1
	v_add_f32_dpp v244, v244, v244 row_half_mirror row_mask:0xf bank_mask:0xf
	s_nop 1
	v_add_f32_dpp v244, v244, v244 row_mirror row_mask:0xf bank_mask:0xf
	s_nop 1
	v_readlane_b32 s38, v244, 0
	v_readlane_b32 s39, v244, 16
	v_readlane_b32 s40, v244, 32
	v_readlane_b32 s41, v244, 48
	s_nop 1
	v_mov_b32_e32 v246, s38
	v_add_f32_e32 v246, s39, v246
	v_add_f32_e32 v246, s40, v246
	v_add_f32_e32 v246, s41, v246
	v_fmamk_f32 v246, v246, 0x3a800000, v17
	v_rsq_f32_e32 v246, v246
	s_nop 0
	v_pk_mul_f32 v[96:97], v[96:97], v[246:247] op_sel_hi:[1,0]
	v_pk_mul_f32 v[98:99], v[98:99], v[246:247] op_sel_hi:[1,0]
	v_pk_mul_f32 v[100:101], v[100:101], v[246:247] op_sel_hi:[1,0]
	v_pk_mul_f32 v[102:103], v[102:103], v[246:247] op_sel_hi:[1,0]
	v_pk_mul_f32 v[104:105], v[104:105], v[246:247] op_sel_hi:[1,0]
	v_pk_mul_f32 v[106:107], v[106:107], v[246:247] op_sel_hi:[1,0]
	v_pk_mul_f32 v[108:109], v[108:109], v[246:247] op_sel_hi:[1,0]
	v_pk_mul_f32 v[110:111], v[110:111], v[246:247] op_sel_hi:[1,0]
	v_cvt_pk_bf16_f32 v96, v96, v97
	v_cvt_pk_bf16_f32 v97, v98, v99
	v_cvt_pk_bf16_f32 v98, v100, v101
	v_cvt_pk_bf16_f32 v99, v102, v103
	v_cvt_pk_bf16_f32 v100, v104, v105
	v_cvt_pk_bf16_f32 v101, v106, v107
	v_cvt_pk_bf16_f32 v102, v108, v109
	v_cvt_pk_bf16_f32 v103, v110, v111
	global_store_dwordx2 v11, v[96:97], s[56:57]
	global_store_dwordx2 v11, v[98:99], s[56:57] offset:512
	global_store_dwordx2 v11, v[100:101], s[56:57] offset:1024
	global_store_dwordx2 v11, v[102:103], s[56:57] offset:1536
	s_add_u32 s56, s56, 0x400000
	s_addc_u32 s57, s57, 0
	s_lshl_b32 s36, s33, 12
	s_add_u32 s36, s6, s36
	s_addc_u32 s37, s7, 0
	global_load_dwordx4 v[96:99], v6, s[36:37] nt
	global_load_dwordx4 v[100:103], v6, s[36:37] offset:1024 nt
	global_load_dwordx4 v[104:107], v6, s[36:37] offset:2048 nt
	global_load_dwordx4 v[108:111], v6, s[36:37] offset:3072 nt
	s_waitcnt vmcnt(8)
	v_pk_mul_f32 v[240:241], v[112:113], v[112:113]
	v_pk_mul_f32 v[242:243], v[120:121], v[120:121]
	v_pk_fma_f32 v[240:241], v[114:115], v[114:115], v[240:241]
	v_pk_fma_f32 v[242:243], v[122:123], v[122:123], v[242:243]
	v_pk_fma_f32 v[240:241], v[116:117], v[116:117], v[240:241]
	v_pk_fma_f32 v[242:243], v[124:125], v[124:125], v[242:243]
	v_pk_fma_f32 v[240:241], v[118:119], v[118:119], v[240:241]
	v_pk_fma_f32 v[242:243], v[126:127], v[126:127], v[242:243]
	v_pk_add_f32 v[240:241], v[240:241], v[242:243]
	s_nop 0
	v_add_f32_e32 v244, v240, v241
	s_nop 1
	v_add_f32_dpp v244, v244, v244 quad_perm:[1,0,3,2] row_mask:0xf bank_mask:0xf
	s_nop 1
	v_add_f32_dpp v244, v244, v244 quad_perm:[2,3,0,1] row_mask:0xf bank_mask:0xf
	s_nop 1
	v_add_f32_dpp v244, v244, v244 row_half_mirror row_mask:0xf bank_mask:0xf
	s_nop 1
	v_add_f32_dpp v244, v244, v244 row_mirror row_mask:0xf bank_mask:0xf
	s_nop 1
	v_readlane_b32 s38, v244, 0
	v_readlane_b32 s39, v244, 16
	v_readlane_b32 s40, v244, 32
	v_readlane_b32 s41, v244, 48
	s_nop 1
	v_mov_b32_e32 v246, s38
	v_add_f32_e32 v246, s39, v246
	v_add_f32_e32 v246, s40, v246
	v_add_f32_e32 v246, s41, v246
	v_fmamk_f32 v246, v246, 0x3a800000, v17
	v_rsq_f32_e32 v246, v246
	s_nop 0
	v_pk_mul_f32 v[112:113], v[112:113], v[246:247] op_sel_hi:[1,0]
	v_pk_mul_f32 v[114:115], v[114:115], v[246:247] op_sel_hi:[1,0]
	v_pk_mul_f32 v[116:117], v[116:117], v[246:247] op_sel_hi:[1,0]
	v_pk_mul_f32 v[118:119], v[118:119], v[246:247] op_sel_hi:[1,0]
	v_pk_mul_f32 v[120:121], v[120:121], v[246:247] op_sel_hi:[1,0]
	v_pk_mul_f32 v[122:123], v[122:123], v[246:247] op_sel_hi:[1,0]
	v_pk_mul_f32 v[124:125], v[124:125], v[246:247] op_sel_hi:[1,0]
	v_pk_mul_f32 v[126:127], v[126:127], v[246:247] op_sel_hi:[1,0]
	v_cvt_pk_bf16_f32 v112, v112, v113
	v_cvt_pk_bf16_f32 v113, v114, v115
	v_cvt_pk_bf16_f32 v114, v116, v117
	v_cvt_pk_bf16_f32 v115, v118, v119
	v_cvt_pk_bf16_f32 v116, v120, v121
	v_cvt_pk_bf16_f32 v117, v122, v123
	v_cvt_pk_bf16_f32 v118, v124, v125
	v_cvt_pk_bf16_f32 v119, v126, v127
	global_store_dwordx2 v11, v[112:113], s[56:57]
	global_store_dwordx2 v11, v[114:115], s[56:57] offset:512
	global_store_dwordx2 v11, v[116:117], s[56:57] offset:1024
	global_store_dwordx2 v11, v[118:119], s[56:57] offset:1536
	s_waitcnt vmcnt(4)
	s_lshl_b32 s56, s33, 11
	s_add_u32 s56, s30, s56
	s_addc_u32 s57, s31, 0
	v_pk_mul_f32 v[240:241], v[96:97], v[96:97]
	v_pk_mul_f32 v[242:243], v[104:105], v[104:105]
	v_pk_fma_f32 v[240:241], v[98:99], v[98:99], v[240:241]
	v_pk_fma_f32 v[242:243], v[106:107], v[106:107], v[242:243]
	v_pk_fma_f32 v[240:241], v[100:101], v[100:101], v[240:241]
	v_pk_fma_f32 v[242:243], v[108:109], v[108:109], v[242:243]
	v_pk_fma_f32 v[240:241], v[102:103], v[102:103], v[240:241]
	v_pk_fma_f32 v[242:243], v[110:111], v[110:111], v[242:243]
	v_pk_add_f32 v[240:241], v[240:241], v[242:243]
	s_nop 0
	v_add_f32_e32 v244, v240, v241
	s_nop 1
	v_add_f32_dpp v244, v244, v244 quad_perm:[1,0,3,2] row_mask:0xf bank_mask:0xf
	s_nop 1
	v_add_f32_dpp v244, v244, v244 quad_perm:[2,3,0,1] row_mask:0xf bank_mask:0xf
	s_nop 1
	v_add_f32_dpp v244, v244, v244 row_half_mirror row_mask:0xf bank_mask:0xf
	s_nop 1
	v_add_f32_dpp v244, v244, v244 row_mirror row_mask:0xf bank_mask:0xf
	s_nop 1
	v_readlane_b32 s38, v244, 0
	v_readlane_b32 s39, v244, 16
	v_readlane_b32 s40, v244, 32
	v_readlane_b32 s41, v244, 48
	s_nop 1
	v_mov_b32_e32 v246, s38
	v_add_f32_e32 v246, s39, v246
	v_add_f32_e32 v246, s40, v246
	v_add_f32_e32 v246, s41, v246
	v_fmamk_f32 v246, v246, 0x3a800000, v17
	v_rsq_f32_e32 v246, v246
	s_nop 0
	v_pk_mul_f32 v[96:97], v[96:97], v[246:247] op_sel_hi:[1,0]
	v_pk_mul_f32 v[98:99], v[98:99], v[246:247] op_sel_hi:[1,0]
	v_pk_mul_f32 v[100:101], v[100:101], v[246:247] op_sel_hi:[1,0]
	v_pk_mul_f32 v[102:103], v[102:103], v[246:247] op_sel_hi:[1,0]
	v_pk_mul_f32 v[104:105], v[104:105], v[246:247] op_sel_hi:[1,0]
	v_pk_mul_f32 v[106:107], v[106:107], v[246:247] op_sel_hi:[1,0]
	v_pk_mul_f32 v[108:109], v[108:109], v[246:247] op_sel_hi:[1,0]
	v_pk_mul_f32 v[110:111], v[110:111], v[246:247] op_sel_hi:[1,0]
	v_cvt_pk_bf16_f32 v96, v96, v97
	v_cvt_pk_bf16_f32 v97, v98, v99
	v_cvt_pk_bf16_f32 v98, v100, v101
	v_cvt_pk_bf16_f32 v99, v102, v103
	v_cvt_pk_bf16_f32 v100, v104, v105
	v_cvt_pk_bf16_f32 v101, v106, v107
	v_cvt_pk_bf16_f32 v102, v108, v109
	v_cvt_pk_bf16_f32 v103, v110, v111
	global_store_dwordx2 v11, v[96:97], s[56:57]
	global_store_dwordx2 v11, v[98:99], s[56:57] offset:512
	global_store_dwordx2 v11, v[100:101], s[56:57] offset:1024
	global_store_dwordx2 v11, v[102:103], s[56:57] offset:1536
	s_branch .Lprep_done
.Lprep_rows8:
	s_waitcnt vmcnt(14)
	v_pk_mul_f32 v[240:241], v[96:97], v[96:97]
	v_pk_mul_f32 v[242:243], v[104:105], v[104:105]
	v_pk_fma_f32 v[240:241], v[98:99], v[98:99], v[240:241]
	v_pk_fma_f32 v[242:243], v[106:107], v[106:107], v[242:243]
	v_pk_fma_f32 v[240:241], v[100:101], v[100:101], v[240:241]
	v_pk_fma_f32 v[242:243], v[108:109], v[108:109], v[242:243]
	v_pk_fma_f32 v[240:241], v[102:103], v[102:103], v[240:241]
	v_pk_fma_f32 v[242:243], v[110:111], v[110:111], v[242:243]
	v_pk_add_f32 v[240:241], v[240:241], v[242:243]
	s_nop 0
	v_add_f32_e32 v244, v240, v241
	s_nop 1
	v_add_f32_dpp v244, v244, v244 quad_perm:[1,0,3,2] row_mask:0xf bank_mask:0xf
	s_nop 1
	v_add_f32_dpp v244, v244, v244 quad_perm:[2,3,0,1] row_mask:0xf bank_mask:0xf
	s_nop 1
	v_add_f32_dpp v244, v244, v244 row_half_mirror row_mask:0xf bank_mask:0xf
	s_nop 1
	v_add_f32_dpp v244, v244, v244 row_mirror row_mask:0xf bank_mask:0xf
	s_nop 1
	v_readlane_b32 s38, v244, 0
	v_readlane_b32 s39, v244, 16
	v_readlane_b32 s40, v244, 32
	v_readlane_b32 s41, v244, 48
	s_nop 1
	v_mov_b32_e32 v246, s38
	v_add_f32_e32 v246, s39, v246
	v_add_f32_e32 v246, s40, v246
	v_add_f32_e32 v246, s41, v246
	v_fmamk_f32 v246, v246, 0x3a800000, v17
	v_rsq_f32_e32 v246, v246
	s_nop 0
	v_pk_mul_f32 v[96:97], v[96:97], v[246:247] op_sel_hi:[1,0]
	v_pk_mul_f32 v[98:99], v[98:99], v[246:247] op_sel_hi:[1,0]
	v_pk_mul_f32 v[100:101], v[100:101], v[246:247] op_sel_hi:[1,0]
	v_pk_mul_f32 v[102:103], v[102:103], v[246:247] op_sel_hi:[1,0]
	v_pk_mul_f32 v[104:105], v[104:105], v[246:247] op_sel_hi:[1,0]
	v_pk_mul_f32 v[106:107], v[106:107], v[246:247] op_sel_hi:[1,0]
	v_pk_mul_f32 v[108:109], v[108:109], v[246:247] op_sel_hi:[1,0]
	v_pk_mul_f32 v[110:111], v[110:111], v[246:247] op_sel_hi:[1,0]
	v_cvt_pk_bf16_f32 v96, v96, v97
	v_cvt_pk_bf16_f32 v97, v98, v99
	v_cvt_pk_bf16_f32 v98, v100, v101
	v_cvt_pk_bf16_f32 v99, v102, v103
	v_cvt_pk_bf16_f32 v100, v104, v105
	v_cvt_pk_bf16_f32 v101, v106, v107
	v_cvt_pk_bf16_f32 v102, v108, v109
	v_cvt_pk_bf16_f32 v103, v110, v111
	global_store_dwordx2 v11, v[96:97], s[56:57]
	global_store_dwordx2 v11, v[98:99], s[56:57] offset:512
	global_store_dwordx2 v11, v[100:101], s[56:57] offset:1024
	global_store_dwordx2 v11, v[102:103], s[56:57] offset:1536
	s_add_u32 s56, s56, 0x400000
	s_addc_u32 s57, s57, 0
	global_load_dwordx4 v[96:99], v6, s[36:37] nt
	global_load_dwordx4 v[100:103], v6, s[36:37] offset:1024 nt
	global_load_dwordx4 v[104:107], v6, s[36:37] offset:2048 nt
	global_load_dwordx4 v[108:111], v6, s[36:37] offset:3072 nt
	s_add_u32 s36, s36, 0x800000
	s_addc_u32 s37, s37, 0
	s_waitcnt vmcnt(18)
	v_pk_mul_f32 v[240:241], v[112:113], v[112:113]
	v_pk_mul_f32 v[242:243], v[120:121], v[120:121]
	v_pk_fma_f32 v[240:241], v[114:115], v[114:115], v[240:241]
	v_pk_fma_f32 v[242:243], v[122:123], v[122:123], v[242:243]
	v_pk_fma_f32 v[240:241], v[116:117], v[116:117], v[240:241]
	v_pk_fma_f32 v[242:243], v[124:125], v[124:125], v[242:243]
	v_pk_fma_f32 v[240:241], v[118:119], v[118:119], v[240:241]
	v_pk_fma_f32 v[242:243], v[126:127], v[126:127], v[242:243]
	v_pk_add_f32 v[240:241], v[240:241], v[242:243]
	s_nop 0
	v_add_f32_e32 v244, v240, v241
	s_nop 1
	v_add_f32_dpp v244, v244, v244 quad_perm:[1,0,3,2] row_mask:0xf bank_mask:0xf
	s_nop 1
	v_add_f32_dpp v244, v244, v244 quad_perm:[2,3,0,1] row_mask:0xf bank_mask:0xf
	s_nop 1
	v_add_f32_dpp v244, v244, v244 row_half_mirror row_mask:0xf bank_mask:0xf
	s_nop 1
	v_add_f32_dpp v244, v244, v244 row_mirror row_mask:0xf bank_mask:0xf
	s_nop 1
	v_readlane_b32 s38, v244, 0
	v_readlane_b32 s39, v244, 16
	v_readlane_b32 s40, v244, 32
	v_readlane_b32 s41, v244, 48
	s_nop 1
	v_mov_b32_e32 v246, s38
	v_add_f32_e32 v246, s39, v246
	v_add_f32_e32 v246, s40, v246
	v_add_f32_e32 v246, s41, v246
	v_fmamk_f32 v246, v246, 0x3a800000, v17
	v_rsq_f32_e32 v246, v246
	s_nop 0
	v_pk_mul_f32 v[112:113], v[112:113], v[246:247] op_sel_hi:[1,0]
	v_pk_mul_f32 v[114:115], v[114:115], v[246:247] op_sel_hi:[1,0]
	v_pk_mul_f32 v[116:117], v[116:117], v[246:247] op_sel_hi:[1,0]
	v_pk_mul_f32 v[118:119], v[118:119], v[246:247] op_sel_hi:[1,0]
	v_pk_mul_f32 v[120:121], v[120:121], v[246:247] op_sel_hi:[1,0]
	v_pk_mul_f32 v[122:123], v[122:123], v[246:247] op_sel_hi:[1,0]
	v_pk_mul_f32 v[124:125], v[124:125], v[246:247] op_sel_hi:[1,0]
	v_pk_mul_f32 v[126:127], v[126:127], v[246:247] op_sel_hi:[1,0]
	v_cvt_pk_bf16_f32 v112, v112, v113
	v_cvt_pk_bf16_f32 v113, v114, v115
	v_cvt_pk_bf16_f32 v114, v116, v117
	v_cvt_pk_bf16_f32 v115, v118, v119
	v_cvt_pk_bf16_f32 v116, v120, v121
	v_cvt_pk_bf16_f32 v117, v122, v123
	v_cvt_pk_bf16_f32 v118, v124, v125
	v_cvt_pk_bf16_f32 v119, v126, v127
	global_store_dwordx2 v11, v[112:113], s[56:57]
	global_store_dwordx2 v11, v[114:115], s[56:57] offset:512
	global_store_dwordx2 v11, v[116:117], s[56:57] offset:1024
	global_store_dwordx2 v11, v[118:119], s[56:57] offset:1536
	s_add_u32 s56, s56, 0x400000
	s_addc_u32 s57, s57, 0
	global_load_dwordx4 v[112:115], v6, s[36:37] nt
	global_load_dwordx4 v[116:119], v6, s[36:37] offset:1024 nt
	global_load_dwordx4 v[120:123], v6, s[36:37] offset:2048 nt
	global_load_dwordx4 v[124:127], v6, s[36:37] offset:3072 nt
	s_add_u32 s36, s36, 0x800000
	s_addc_u32 s37, s37, 0
	s_waitcnt vmcnt(8)
	v_pk_mul_f32 v[240:241], v[96:97], v[96:97]
	v_pk_mul_f32 v[242:243], v[104:105], v[104:105]
	v_pk_fma_f32 v[240:241], v[98:99], v[98:99], v[240:241]
	v_pk_fma_f32 v[242:243], v[106:107], v[106:107], v[242:243]
	v_pk_fma_f32 v[240:241], v[100:101], v[100:101], v[240:241]
	v_pk_fma_f32 v[242:243], v[108:109], v[108:109], v[242:243]
	v_pk_fma_f32 v[240:241], v[102:103], v[102:103], v[240:241]
	v_pk_fma_f32 v[242:243], v[110:111], v[110:111], v[242:243]
	v_pk_add_f32 v[240:241], v[240:241], v[242:243]
	s_nop 0
	v_add_f32_e32 v244, v240, v241
	s_nop 1
	v_add_f32_dpp v244, v244, v244 quad_perm:[1,0,3,2] row_mask:0xf bank_mask:0xf
	s_nop 1
	v_add_f32_dpp v244, v244, v244 quad_perm:[2,3,0,1] row_mask:0xf bank_mask:0xf
	s_nop 1
	v_add_f32_dpp v244, v244, v244 row_half_mirror row_mask:0xf bank_mask:0xf
	s_nop 1
	v_add_f32_dpp v244, v244, v244 row_mirror row_mask:0xf bank_mask:0xf
	s_nop 1
	v_readlane_b32 s38, v244, 0
	v_readlane_b32 s39, v244, 16
	v_readlane_b32 s40, v244, 32
	v_readlane_b32 s41, v244, 48
	s_nop 1
	v_mov_b32_e32 v246, s38
	v_add_f32_e32 v246, s39, v246
	v_add_f32_e32 v246, s40, v246
	v_add_f32_e32 v246, s41, v246
	v_fmamk_f32 v246, v246, 0x3a800000, v17
	v_rsq_f32_e32 v246, v246
	s_nop 0
	v_pk_mul_f32 v[96:97], v[96:97], v[246:247] op_sel_hi:[1,0]
	v_pk_mul_f32 v[98:99], v[98:99], v[246:247] op_sel_hi:[1,0]
	v_pk_mul_f32 v[100:101], v[100:101], v[246:247] op_sel_hi:[1,0]
	v_pk_mul_f32 v[102:103], v[102:103], v[246:247] op_sel_hi:[1,0]
	v_pk_mul_f32 v[104:105], v[104:105], v[246:247] op_sel_hi:[1,0]
	v_pk_mul_f32 v[106:107], v[106:107], v[246:247] op_sel_hi:[1,0]
	v_pk_mul_f32 v[108:109], v[108:109], v[246:247] op_sel_hi:[1,0]
	v_pk_mul_f32 v[110:111], v[110:111], v[246:247] op_sel_hi:[1,0]
	v_cvt_pk_bf16_f32 v96, v96, v97
	v_cvt_pk_bf16_f32 v97, v98, v99
	v_cvt_pk_bf16_f32 v98, v100, v101
	v_cvt_pk_bf16_f32 v99, v102, v103
	v_cvt_pk_bf16_f32 v100, v104, v105
	v_cvt_pk_bf16_f32 v101, v106, v107
	v_cvt_pk_bf16_f32 v102, v108, v109
	v_cvt_pk_bf16_f32 v103, v110, v111
	global_store_dwordx2 v11, v[96:97], s[56:57]
	global_store_dwordx2 v11, v[98:99], s[56:57] offset:512
	global_store_dwordx2 v11, v[100:101], s[56:57] offset:1024
	global_store_dwordx2 v11, v[102:103], s[56:57] offset:1536
	s_add_u32 s56, s56, 0x400000
	s_addc_u32 s57, s57, 0
	global_load_dwordx4 v[96:99], v6, s[36:37] nt
	global_load_dwordx4 v[100:103], v6, s[36:37] offset:1024 nt
	global_load_dwordx4 v[104:107], v6, s[36:37] offset:2048 nt
	global_load_dwordx4 v[108:111], v6, s[36:37] offset:3072 nt
	s_add_u32 s36, s36, 0x800000
	s_addc_u32 s37, s37, 0
	s_waitcnt vmcnt(8)
	v_pk_mul_f32 v[240:241], v[112:113], v[112:113]
	v_pk_mul_f32 v[242:243], v[120:121], v[120:121]
	v_pk_fma_f32 v[240:241], v[114:115], v[114:115], v[240:241]
	v_pk_fma_f32 v[242:243], v[122:123], v[122:123], v[242:243]
	v_pk_fma_f32 v[240:241], v[116:117], v[116:117], v[240:241]
	v_pk_fma_f32 v[242:243], v[124:125], v[124:125], v[242:243]
	v_pk_fma_f32 v[240:241], v[118:119], v[118:119], v[240:241]
	v_pk_fma_f32 v[242:243], v[126:127], v[126:127], v[242:243]
	v_pk_add_f32 v[240:241], v[240:241], v[242:243]
	s_nop 0
	v_add_f32_e32 v244, v240, v241
	s_nop 1
	v_add_f32_dpp v244, v244, v244 quad_perm:[1,0,3,2] row_mask:0xf bank_mask:0xf
	s_nop 1
	v_add_f32_dpp v244, v244, v244 quad_perm:[2,3,0,1] row_mask:0xf bank_mask:0xf
	s_nop 1
	v_add_f32_dpp v244, v244, v244 row_half_mirror row_mask:0xf bank_mask:0xf
	s_nop 1
	v_add_f32_dpp v244, v244, v244 row_mirror row_mask:0xf bank_mask:0xf
	s_nop 1
	v_readlane_b32 s38, v244, 0
	v_readlane_b32 s39, v244, 16
	v_readlane_b32 s40, v244, 32
	v_readlane_b32 s41, v244, 48
	s_nop 1
	v_mov_b32_e32 v246, s38
	v_add_f32_e32 v246, s39, v246
	v_add_f32_e32 v246, s40, v246
	v_add_f32_e32 v246, s41, v246
	v_fmamk_f32 v246, v246, 0x3a800000, v17
	v_rsq_f32_e32 v246, v246
	s_nop 0
	v_pk_mul_f32 v[112:113], v[112:113], v[246:247] op_sel_hi:[1,0]
	v_pk_mul_f32 v[114:115], v[114:115], v[246:247] op_sel_hi:[1,0]
	v_pk_mul_f32 v[116:117], v[116:117], v[246:247] op_sel_hi:[1,0]
	v_pk_mul_f32 v[118:119], v[118:119], v[246:247] op_sel_hi:[1,0]
	v_pk_mul_f32 v[120:121], v[120:121], v[246:247] op_sel_hi:[1,0]
	v_pk_mul_f32 v[122:123], v[122:123], v[246:247] op_sel_hi:[1,0]
	v_pk_mul_f32 v[124:125], v[124:125], v[246:247] op_sel_hi:[1,0]
	v_pk_mul_f32 v[126:127], v[126:127], v[246:247] op_sel_hi:[1,0]
	v_cvt_pk_bf16_f32 v112, v112, v113
	v_cvt_pk_bf16_f32 v113, v114, v115
	v_cvt_pk_bf16_f32 v114, v116, v117
	v_cvt_pk_bf16_f32 v115, v118, v119
	v_cvt_pk_bf16_f32 v116, v120, v121
	v_cvt_pk_bf16_f32 v117, v122, v123
	v_cvt_pk_bf16_f32 v118, v124, v125
	v_cvt_pk_bf16_f32 v119, v126, v127
	global_store_dwordx2 v11, v[112:113], s[56:57]
	global_store_dwordx2 v11, v[114:115], s[56:57] offset:512
	global_store_dwordx2 v11, v[116:117], s[56:57] offset:1024
	global_store_dwordx2 v11, v[118:119], s[56:57] offset:1536
	s_add_u32 s56, s56, 0x400000
	s_addc_u32 s57, s57, 0
	global_load_dwordx4 v[112:115], v6, s[36:37] nt
	global_load_dwordx4 v[116:119], v6, s[36:37] offset:1024 nt
	global_load_dwordx4 v[120:123], v6, s[36:37] offset:2048 nt
	global_load_dwordx4 v[124:127], v6, s[36:37] offset:3072 nt
	s_add_u32 s36, s36, 0x800000
	s_addc_u32 s37, s37, 0
	s_waitcnt vmcnt(8)
	v_pk_mul_f32 v[240:241], v[96:97], v[96:97]
	v_pk_mul_f32 v[242:243], v[104:105], v[104:105]
	v_pk_fma_f32 v[240:241], v[98:99], v[98:99], v[240:241]
	v_pk_fma_f32 v[242:243], v[106:107], v[106:107], v[242:243]
	v_pk_fma_f32 v[240:241], v[100:101], v[100:101], v[240:241]
	v_pk_fma_f32 v[242:243], v[108:109], v[108:109], v[242:243]
	v_pk_fma_f32 v[240:241], v[102:103], v[102:103], v[240:241]
	v_pk_fma_f32 v[242:243], v[110:111], v[110:111], v[242:243]
	v_pk_add_f32 v[240:241], v[240:241], v[242:243]
	s_nop 0
	v_add_f32_e32 v244, v240, v241
	s_nop 1
	v_add_f32_dpp v244, v244, v244 quad_perm:[1,0,3,2] row_mask:0xf bank_mask:0xf
	s_nop 1
	v_add_f32_dpp v244, v244, v244 quad_perm:[2,3,0,1] row_mask:0xf bank_mask:0xf
	s_nop 1
	v_add_f32_dpp v244, v244, v244 row_half_mirror row_mask:0xf bank_mask:0xf
	s_nop 1
	v_add_f32_dpp v244, v244, v244 row_mirror row_mask:0xf bank_mask:0xf
	s_nop 1
	v_readlane_b32 s38, v244, 0
	v_readlane_b32 s39, v244, 16
	v_readlane_b32 s40, v244, 32
	v_readlane_b32 s41, v244, 48
	s_nop 1
	v_mov_b32_e32 v246, s38
	v_add_f32_e32 v246, s39, v246
	v_add_f32_e32 v246, s40, v246
	v_add_f32_e32 v246, s41, v246
	v_fmamk_f32 v246, v246, 0x3a800000, v17
	v_rsq_f32_e32 v246, v246
	s_nop 0
	v_pk_mul_f32 v[96:97], v[96:97], v[246:247] op_sel_hi:[1,0]
	v_pk_mul_f32 v[98:99], v[98:99], v[246:247] op_sel_hi:[1,0]
	v_pk_mul_f32 v[100:101], v[100:101], v[246:247] op_sel_hi:[1,0]
	v_pk_mul_f32 v[102:103], v[102:103], v[246:247] op_sel_hi:[1,0]
	v_pk_mul_f32 v[104:105], v[104:105], v[246:247] op_sel_hi:[1,0]
	v_pk_mul_f32 v[106:107], v[106:107], v[246:247] op_sel_hi:[1,0]
	v_pk_mul_f32 v[108:109], v[108:109], v[246:247] op_sel_hi:[1,0]
	v_pk_mul_f32 v[110:111], v[110:111], v[246:247] op_sel_hi:[1,0]
	v_cvt_pk_bf16_f32 v96, v96, v97
	v_cvt_pk_bf16_f32 v97, v98, v99
	v_cvt_pk_bf16_f32 v98, v100, v101
	v_cvt_pk_bf16_f32 v99, v102, v103
	v_cvt_pk_bf16_f32 v100, v104, v105
	v_cvt_pk_bf16_f32 v101, v106, v107
	v_cvt_pk_bf16_f32 v102, v108, v109
	v_cvt_pk_bf16_f32 v103, v110, v111
	global_store_dwordx2 v11, v[96:97], s[56:57]
	global_store_dwordx2 v11, v[98:99], s[56:57] offset:512
	global_store_dwordx2 v11, v[100:101], s[56:57] offset:1024
	global_store_dwordx2 v11, v[102:103], s[56:57] offset:1536
	s_add_u32 s56, s56, 0x400000
	s_addc_u32 s57, s57, 0
	global_load_dwordx4 v[96:99], v6, s[36:37] nt
	global_load_dwordx4 v[100:103], v6, s[36:37] offset:1024 nt
	global_load_dwordx4 v[104:107], v6, s[36:37] offset:2048 nt
	global_load_dwordx4 v[108:111], v6, s[36:37] offset:3072 nt
	s_add_u32 s36, s36, 0x800000
	s_addc_u32 s37, s37, 0
	s_waitcnt vmcnt(8)
	v_pk_mul_f32 v[240:241], v[112:113], v[112:113]
	v_pk_mul_f32 v[242:243], v[120:121], v[120:121]
	v_pk_fma_f32 v[240:241], v[114:115], v[114:115], v[240:241]
	v_pk_fma_f32 v[242:243], v[122:123], v[122:123], v[242:243]
	v_pk_fma_f32 v[240:241], v[116:117], v[116:117], v[240:241]
	v_pk_fma_f32 v[242:243], v[124:125], v[124:125], v[242:243]
	v_pk_fma_f32 v[240:241], v[118:119], v[118:119], v[240:241]
	v_pk_fma_f32 v[242:243], v[126:127], v[126:127], v[242:243]
	v_pk_add_f32 v[240:241], v[240:241], v[242:243]
	s_nop 0
	v_add_f32_e32 v244, v240, v241
	s_nop 1
	v_add_f32_dpp v244, v244, v244 quad_perm:[1,0,3,2] row_mask:0xf bank_mask:0xf
	s_nop 1
	v_add_f32_dpp v244, v244, v244 quad_perm:[2,3,0,1] row_mask:0xf bank_mask:0xf
	s_nop 1
	v_add_f32_dpp v244, v244, v244 row_half_mirror row_mask:0xf bank_mask:0xf
	s_nop 1
	v_add_f32_dpp v244, v244, v244 row_mirror row_mask:0xf bank_mask:0xf
	s_nop 1
	v_readlane_b32 s38, v244, 0
	v_readlane_b32 s39, v244, 16
	v_readlane_b32 s40, v244, 32
	v_readlane_b32 s41, v244, 48
	s_nop 1
	v_mov_b32_e32 v246, s38
	v_add_f32_e32 v246, s39, v246
	v_add_f32_e32 v246, s40, v246
	v_add_f32_e32 v246, s41, v246
	v_fmamk_f32 v246, v246, 0x3a800000, v17
	v_rsq_f32_e32 v246, v246
	s_nop 0
	v_pk_mul_f32 v[112:113], v[112:113], v[246:247] op_sel_hi:[1,0]
	v_pk_mul_f32 v[114:115], v[114:115], v[246:247] op_sel_hi:[1,0]
	v_pk_mul_f32 v[116:117], v[116:117], v[246:247] op_sel_hi:[1,0]
	v_pk_mul_f32 v[118:119], v[118:119], v[246:247] op_sel_hi:[1,0]
	v_pk_mul_f32 v[120:121], v[120:121], v[246:247] op_sel_hi:[1,0]
	v_pk_mul_f32 v[122:123], v[122:123], v[246:247] op_sel_hi:[1,0]
	v_pk_mul_f32 v[124:125], v[124:125], v[246:247] op_sel_hi:[1,0]
	v_pk_mul_f32 v[126:127], v[126:127], v[246:247] op_sel_hi:[1,0]
	v_cvt_pk_bf16_f32 v112, v112, v113
	v_cvt_pk_bf16_f32 v113, v114, v115
	v_cvt_pk_bf16_f32 v114, v116, v117
	v_cvt_pk_bf16_f32 v115, v118, v119
	v_cvt_pk_bf16_f32 v116, v120, v121
	v_cvt_pk_bf16_f32 v117, v122, v123
	v_cvt_pk_bf16_f32 v118, v124, v125
	v_cvt_pk_bf16_f32 v119, v126, v127
	global_store_dwordx2 v11, v[112:113], s[56:57]
	global_store_dwordx2 v11, v[114:115], s[56:57] offset:512
	global_store_dwordx2 v11, v[116:117], s[56:57] offset:1024
	global_store_dwordx2 v11, v[118:119], s[56:57] offset:1536
	s_add_u32 s56, s56, 0x400000
	s_addc_u32 s57, s57, 0
	global_load_dwordx4 v[112:115], v6, s[36:37] nt
	global_load_dwordx4 v[116:119], v6, s[36:37] offset:1024 nt
	global_load_dwordx4 v[120:123], v6, s[36:37] offset:2048 nt
	global_load_dwordx4 v[124:127], v6, s[36:37] offset:3072 nt
	s_waitcnt vmcnt(8)
	v_pk_mul_f32 v[240:241], v[96:97], v[96:97]
	v_pk_mul_f32 v[242:243], v[104:105], v[104:105]
	v_pk_fma_f32 v[240:241], v[98:99], v[98:99], v[240:241]
	v_pk_fma_f32 v[242:243], v[106:107], v[106:107], v[242:243]
	v_pk_fma_f32 v[240:241], v[100:101], v[100:101], v[240:241]
	v_pk_fma_f32 v[242:243], v[108:109], v[108:109], v[242:243]
	v_pk_fma_f32 v[240:241], v[102:103], v[102:103], v[240:241]
	v_pk_fma_f32 v[242:243], v[110:111], v[110:111], v[242:243]
	v_pk_add_f32 v[240:241], v[240:241], v[242:243]
	s_nop 0
	v_add_f32_e32 v244, v240, v241
	s_nop 1
	v_add_f32_dpp v244, v244, v244 quad_perm:[1,0,3,2] row_mask:0xf bank_mask:0xf
	s_nop 1
	v_add_f32_dpp v244, v244, v244 quad_perm:[2,3,0,1] row_mask:0xf bank_mask:0xf
	s_nop 1
	v_add_f32_dpp v244, v244, v244 row_half_mirror row_mask:0xf bank_mask:0xf
	s_nop 1
	v_add_f32_dpp v244, v244, v244 row_mirror row_mask:0xf bank_mask:0xf
	s_nop 1
	v_readlane_b32 s38, v244, 0
	v_readlane_b32 s39, v244, 16
	v_readlane_b32 s40, v244, 32
	v_readlane_b32 s41, v244, 48
	s_nop 1
	v_mov_b32_e32 v246, s38
	v_add_f32_e32 v246, s39, v246
	v_add_f32_e32 v246, s40, v246
	v_add_f32_e32 v246, s41, v246
	v_fmamk_f32 v246, v246, 0x3a800000, v17
	v_rsq_f32_e32 v246, v246
	s_nop 0
	v_pk_mul_f32 v[96:97], v[96:97], v[246:247] op_sel_hi:[1,0]
	v_pk_mul_f32 v[98:99], v[98:99], v[246:247] op_sel_hi:[1,0]
	v_pk_mul_f32 v[100:101], v[100:101], v[246:247] op_sel_hi:[1,0]
	v_pk_mul_f32 v[102:103], v[102:103], v[246:247] op_sel_hi:[1,0]
	v_pk_mul_f32 v[104:105], v[104:105], v[246:247] op_sel_hi:[1,0]
	v_pk_mul_f32 v[106:107], v[106:107], v[246:247] op_sel_hi:[1,0]
	v_pk_mul_f32 v[108:109], v[108:109], v[246:247] op_sel_hi:[1,0]
	v_pk_mul_f32 v[110:111], v[110:111], v[246:247] op_sel_hi:[1,0]
	v_cvt_pk_bf16_f32 v96, v96, v97
	v_cvt_pk_bf16_f32 v97, v98, v99
	v_cvt_pk_bf16_f32 v98, v100, v101
	v_cvt_pk_bf16_f32 v99, v102, v103
	v_cvt_pk_bf16_f32 v100, v104, v105
	v_cvt_pk_bf16_f32 v101, v106, v107
	v_cvt_pk_bf16_f32 v102, v108, v109
	v_cvt_pk_bf16_f32 v103, v110, v111
	global_store_dwordx2 v11, v[96:97], s[56:57]
	global_store_dwordx2 v11, v[98:99], s[56:57] offset:512
	global_store_dwordx2 v11, v[100:101], s[56:57] offset:1024
	global_store_dwordx2 v11, v[102:103], s[56:57] offset:1536
	s_add_u32 s56, s56, 0x400000
	s_addc_u32 s57, s57, 0
	s_waitcnt vmcnt(4)
	v_pk_mul_f32 v[240:241], v[112:113], v[112:113]
	v_pk_mul_f32 v[242:243], v[120:121], v[120:121]
	v_pk_fma_f32 v[240:241], v[114:115], v[114:115], v[240:241]
	v_pk_fma_f32 v[242:243], v[122:123], v[122:123], v[242:243]
	v_pk_fma_f32 v[240:241], v[116:117], v[116:117], v[240:241]
	v_pk_fma_f32 v[242:243], v[124:125], v[124:125], v[242:243]
	v_pk_fma_f32 v[240:241], v[118:119], v[118:119], v[240:241]
	v_pk_fma_f32 v[242:243], v[126:127], v[126:127], v[242:243]
	v_pk_add_f32 v[240:241], v[240:241], v[242:243]
	s_nop 0
	v_add_f32_e32 v244, v240, v241
	s_nop 1
	v_add_f32_dpp v244, v244, v244 quad_perm:[1,0,3,2] row_mask:0xf bank_mask:0xf
	s_nop 1
	v_add_f32_dpp v244, v244, v244 quad_perm:[2,3,0,1] row_mask:0xf bank_mask:0xf
	s_nop 1
	v_add_f32_dpp v244, v244, v244 row_half_mirror row_mask:0xf bank_mask:0xf
	s_nop 1
	v_add_f32_dpp v244, v244, v244 row_mirror row_mask:0xf bank_mask:0xf
	s_nop 1
	v_readlane_b32 s38, v244, 0
	v_readlane_b32 s39, v244, 16
	v_readlane_b32 s40, v244, 32
	v_readlane_b32 s41, v244, 48
	s_nop 1
	v_mov_b32_e32 v246, s38
	v_add_f32_e32 v246, s39, v246
	v_add_f32_e32 v246, s40, v246
	v_add_f32_e32 v246, s41, v246
	v_fmamk_f32 v246, v246, 0x3a800000, v17
	v_rsq_f32_e32 v246, v246
	s_nop 0
	v_pk_mul_f32 v[112:113], v[112:113], v[246:247] op_sel_hi:[1,0]
	v_pk_mul_f32 v[114:115], v[114:115], v[246:247] op_sel_hi:[1,0]
	v_pk_mul_f32 v[116:117], v[116:117], v[246:247] op_sel_hi:[1,0]
	v_pk_mul_f32 v[118:119], v[118:119], v[246:247] op_sel_hi:[1,0]
	v_pk_mul_f32 v[120:121], v[120:121], v[246:247] op_sel_hi:[1,0]
	v_pk_mul_f32 v[122:123], v[122:123], v[246:247] op_sel_hi:[1,0]
	v_pk_mul_f32 v[124:125], v[124:125], v[246:247] op_sel_hi:[1,0]
	v_pk_mul_f32 v[126:127], v[126:127], v[246:247] op_sel_hi:[1,0]
	v_cvt_pk_bf16_f32 v112, v112, v113
	v_cvt_pk_bf16_f32 v113, v114, v115
	v_cvt_pk_bf16_f32 v114, v116, v117
	v_cvt_pk_bf16_f32 v115, v118, v119
	v_cvt_pk_bf16_f32 v116, v120, v121
	v_cvt_pk_bf16_f32 v117, v122, v123
	v_cvt_pk_bf16_f32 v118, v124, v125
	v_cvt_pk_bf16_f32 v119, v126, v127
	global_store_dwordx2 v11, v[112:113], s[56:57]
	global_store_dwordx2 v11, v[114:115], s[56:57] offset:512
	global_store_dwordx2 v11, v[116:117], s[56:57] offset:1024
	global_store_dwordx2 v11, v[118:119], s[56:57] offset:1536

.LBB0_331:
	s_or_b64 exec, exec, s[18:19]
	v_mul_lo_u32 v6, s17, v1
	v_mul_lo_u32 v7, s16, v4
	v_mad_u64_u32 v[4:5], s[6:7], s16, v1, 0
	v_add3_u32 v5, v5, v7, v6
	v_lshl_add_u64 v[2:3], v[4:5], 1, v[2:3]
	v_cvt_pk_bf16_f32 v4, v114, v115
	v_cvt_pk_bf16_f32 v5, v116, v117
	global_store_dwordx2 v[2:3], v[4:5], off
	v_cvt_pk_bf16_f32 v4, v106, v107
	v_cvt_pk_bf16_f32 v5, v108, v109
	global_store_dwordx2 v[2:3], v[4:5], off offset:32
	v_cvt_pk_bf16_f32 v4, v110, v111
	v_cvt_pk_bf16_f32 v5, v112, v113
	s_waitcnt vmcnt(8)
	v_mov_b64_e32 v[78:79], v[98:99]
	v_mov_b64_e32 v[82:83], v[94:95]
	v_mov_b64_e32 v[70:71], v[90:91]
	v_mov_b64_e32 v[74:75], v[86:87]
	global_store_dwordx2 v[2:3], v[4:5], off offset:64
	v_cvt_pk_bf16_f32 v4, v102, v103
	v_cvt_pk_bf16_f32 v5, v104, v105
	s_andn2_b64 vcc, exec, s[26:27]
	v_mov_b64_e32 v[80:81], v[100:101]
	v_mov_b64_e32 v[84:85], v[96:97]
	v_mov_b64_e32 v[72:73], v[92:93]
	v_mov_b64_e32 v[76:77], v[88:89]
	s_mov_b32 s16, s49
	s_mov_b32 s17, s29
	s_mov_b32 s18, s48
	s_mov_b64 s[20:21], s[30:31]
	s_mov_b32 s14, s28
	global_store_dwordx2 v[2:3], v[4:5], off offset:96
	s_barrier
	s_cbranch_vccz .LBB0_375
